# v16 + MoBA chunk tails: transposed V reads issued as soon as their score registers are consumed by the exps (counted lgkmcnt before each PV MFMA)
# speedup vs baseline: 1.0136x; 1.0022x over previous
; #define LAS __attribute__((address_space(3)))
; __device__ __forceinline__ unsigned pk2(float lo, float hi) { f32x2_t v = {lo, hi}; bf16x2_t b = __builtin_convertvector(v, bf16x2_t); return __builtin_bit_cast(unsigned, b); }
; __device__ __forceinline__ float xor32_sum(float v) { auto rr = __builtin_amdgcn_permlane32_swap(__float_as_uint(v), __float_as_uint(v), false, false); return __uint_as_float(rr[0]) + __uint_as_float(rr[1]); }
; #define MFMA32(a, b, c) __builtin_amdgcn_mfma_f32_32x32x16_bf16((a), (b), (c), 0, 0, 0)
; __device__ __forceinline__ s16x4 vtr(const LAS unsigned char* p) { return __builtin_bit_cast(s16x4, __builtin_amdgcn_ds_read_tr16_b64_v4i16((LAS v4i16_t*)p)); }
; __device__ __forceinline__ void read_vf_at(VF& f, const LAS unsigned char* vb, const WaveCtx& c) {
; #pragma unroll
;     for (int dt = 0; dt < 2; ++dt)
; #pragma unroll
;         for (int s2 = 0; s2 < 2; ++s2) {
;             const LAS unsigned char* a = vb + c.troff + (16 * s2) * VROW + dt * 64;
;             const s16x4 lo = vtr(a), hi = vtr(a + 8 * VROW);
;             f.v[dt][s2] = (bf16x8){lo[0], lo[1], lo[2], lo[3], hi[0], hi[1], hi[2], hi[3]};
;         }
; }
; __device__ __forceinline__ void pv(f32x16 (&o)[2], const f32x16& p, const VF& f) {
;     bf16x8 pb[2];
; #pragma unroll
;     for (int s2 = 0; s2 < 2; ++s2) {
;         u32x4 w; w.x = pk2(p[8 * s2 + 0], p[8 * s2 + 1]); w.y = pk2(p[8 * s2 + 2], p[8 * s2 + 3]); w.z = pk2(p[8 * s2 + 4], p[8 * s2 + 5]); w.w = pk2(p[8 * s2 + 6], p[8 * s2 + 7]);
;         pb[s2] = __builtin_bit_cast(bf16x8, w);
;     }
; #pragma unroll
;     for (int s2 = 0; s2 < 2; ++s2)
; #pragma unroll
;         for (int dt = 0; dt < 2; ++dt) o[dt] = MFMA32(f.v[dt][s2], pb[s2], o[dt]);
; }
; __device__ __forceinline__ void soft_compute_lds(SoftState& st, const bf16x8 (&qf)[4], const LAS unsigned char* kc, const LAS unsigned char* vc, int k0, int qp, bool lane_ok, bool diag, const WaveCtx& c) {
;     ...
;     float ps = 0.f;
; #pragma unroll
;     for (int r = 0; r < 16; ++r) { const float p = __builtin_amdgcn_exp2f(s[r]); s[r] = p; ps += p; }
;     st.l += xor32_sum(ps);
;     VF vf; read_vf_at(vf, vc, c);
;     pv(st.o, s, vf);
.LBB0_491:
	v_add_u32_e32 v238, s97, v159
	v_exp_f32_e32 v163, v98
	v_exp_f32_e32 v164, v99
	v_exp_f32_e32 v165, v100
	v_exp_f32_e32 v166, v101
	ds_read_b64_tr_b16 v[98:99], v238 offset:18432
	ds_read_b64_tr_b16 v[100:101], v238 offset:19584
	v_add_f32_e32 v239, 0, v163
	v_exp_f32_e32 v167, v102
	v_add_f32_e32 v239, v164, v239
	v_exp_f32_e32 v168, v103
	v_add_f32_e32 v239, v165, v239
	v_exp_f32_e32 v169, v104
	v_add_f32_e32 v239, v166, v239
	v_exp_f32_e32 v170, v105
	ds_read_b64_tr_b16 v[102:103], v238 offset:20736
	ds_read_b64_tr_b16 v[104:105], v238 offset:21888
	v_add_f32_e32 v239, v167, v239
	v_exp_f32_e32 v171, v106
	v_add_f32_e32 v239, v168, v239
	v_exp_f32_e32 v172, v107
	v_add_f32_e32 v239, v169, v239
	v_exp_f32_e32 v173, v108
	v_add_f32_e32 v239, v170, v239
	v_exp_f32_e32 v174, v109
	ds_read_b64_tr_b16 v[106:107], v238 offset:18496
	ds_read_b64_tr_b16 v[108:109], v238 offset:19648
	v_add_f32_e32 v239, v171, v239
	v_exp_f32_e32 v175, v110
	v_add_f32_e32 v239, v172, v239
	v_exp_f32_e32 v176, v111
	v_add_f32_e32 v239, v173, v239
	v_exp_f32_e32 v177, v112
	v_add_f32_e32 v239, v174, v239
	v_exp_f32_e32 v178, v113
	ds_read_b64_tr_b16 v[110:111], v238 offset:20800
	ds_read_b64_tr_b16 v[112:113], v238 offset:21952
	v_add_f32_e32 v239, v175, v239
	v_add_f32_e32 v239, v176, v239
	v_add_f32_e32 v239, v177, v239
	v_add_f32_e32 v239, v178, v239
	v_mov_b32_e32 v240, v239
	s_nop 1
	v_permlane32_swap_b32_e32 v239, v240
	v_add_f32_e32 v239, v239, v240
	v_add_f32_e32 v162, v162, v239
	v_cvt_pk_bf16_f32 v164, v163, v164
	v_cvt_pk_bf16_f32 v165, v165, v166
	v_cvt_pk_bf16_f32 v166, v167, v168
	v_cvt_pk_bf16_f32 v167, v169, v170
	v_cvt_pk_bf16_f32 v168, v171, v172
	v_cvt_pk_bf16_f32 v169, v173, v174
	s_waitcnt lgkmcnt(6)
	v_mfma_f32_32x32x16_bf16 v[66:81], v[98:101], v[164:167], v[66:81]
	v_cvt_pk_bf16_f32 v170, v175, v176
	v_cvt_pk_bf16_f32 v171, v177, v178
	s_addk_i32 s97, 0x1200
	s_cmpk_lg_i32 s97, 0x4800
	s_waitcnt lgkmcnt(2)
	v_mfma_f32_32x32x16_bf16 v[48:63], v[106:109], v[164:167], v[48:63]
	s_nop 0
	v_mfma_f32_32x32x16_bf16 v[66:81], v[102:105], v[168:171], v[66:81]
	s_waitcnt lgkmcnt(0)
	v_mfma_f32_32x32x16_bf16 v[48:63], v[110:113], v[168:171], v[48:63]
	s_cbranch_scc0 .LBB0_496

; #define LAS __attribute__((address_space(3)))
; __device__ __forceinline__ unsigned pk2(float lo, float hi) { f32x2_t v = {lo, hi}; bf16x2_t b = __builtin_convertvector(v, bf16x2_t); return __builtin_bit_cast(unsigned, b); }
; __device__ __forceinline__ float xor32_sum(float v) { auto rr = __builtin_amdgcn_permlane32_swap(__float_as_uint(v), __float_as_uint(v), false, false); return __uint_as_float(rr[0]) + __uint_as_float(rr[1]); }
; #define MFMA32(a, b, c) __builtin_amdgcn_mfma_f32_32x32x16_bf16((a), (b), (c), 0, 0, 0)
; __device__ __forceinline__ s16x4 vtr(const LAS unsigned char* p) { return __builtin_bit_cast(s16x4, __builtin_amdgcn_ds_read_tr16_b64_v4i16((LAS v4i16_t*)p)); }
; __device__ __forceinline__ void read_vf_at(VF& f, const LAS unsigned char* vb, const WaveCtx& c) {
; #pragma unroll
;     for (int dt = 0; dt < 2; ++dt)
; #pragma unroll
;         for (int s2 = 0; s2 < 2; ++s2) {
;             const LAS unsigned char* a = vb + c.troff + (16 * s2) * VROW + dt * 64;
;             const s16x4 lo = vtr(a), hi = vtr(a + 8 * VROW);
;             f.v[dt][s2] = (bf16x8){lo[0], lo[1], lo[2], lo[3], hi[0], hi[1], hi[2], hi[3]};
;         }
; }
; __device__ __forceinline__ void pv(f32x16 (&o)[2], const f32x16& p, const VF& f) {
;     bf16x8 pb[2];
; #pragma unroll
;     for (int s2 = 0; s2 < 2; ++s2) {
;         u32x4 w; w.x = pk2(p[8 * s2 + 0], p[8 * s2 + 1]); w.y = pk2(p[8 * s2 + 2], p[8 * s2 + 3]); w.z = pk2(p[8 * s2 + 4], p[8 * s2 + 5]); w.w = pk2(p[8 * s2 + 6], p[8 * s2 + 7]);
;         pb[s2] = __builtin_bit_cast(bf16x8, w);
;     }
; #pragma unroll
;     for (int s2 = 0; s2 < 2; ++s2)
; #pragma unroll
;         for (int dt = 0; dt < 2; ++dt) o[dt] = MFMA32(f.v[dt][s2], pb[s2], o[dt]);
; }
; __device__ __forceinline__ void soft_compute_lds(SoftState& st, const bf16x8 (&qf)[4], const LAS unsigned char* kc, const LAS unsigned char* vc, int k0, int qp, bool lane_ok, bool diag, const WaveCtx& c) {
;     ...
;     float ps = 0.f;
; #pragma unroll
;     for (int r = 0; r < 16; ++r) { const float p = __builtin_amdgcn_exp2f(s[r]); s[r] = p; ps += p; }
;     st.l += xor32_sum(ps);
;     VF vf; read_vf_at(vf, vc, c);
;     pv(st.o, s, vf);
.LBB0_498:
	v_add_u32_e32 v238, s35, v159
	v_exp_f32_e32 v66, v48
	v_exp_f32_e32 v67, v49
	v_exp_f32_e32 v68, v50
	v_exp_f32_e32 v69, v51
	ds_read_b64_tr_b16 v[48:49], v238 offset:18432
	ds_read_b64_tr_b16 v[50:51], v238 offset:19584
	v_add_f32_e32 v239, 0, v66
	v_exp_f32_e32 v70, v52
	v_add_f32_e32 v239, v67, v239
	v_exp_f32_e32 v71, v53
	v_add_f32_e32 v239, v68, v239
	v_exp_f32_e32 v72, v54
	v_add_f32_e32 v239, v69, v239
	v_exp_f32_e32 v73, v55
	ds_read_b64_tr_b16 v[52:53], v238 offset:20736
	ds_read_b64_tr_b16 v[54:55], v238 offset:21888
	v_add_f32_e32 v239, v70, v239
	v_exp_f32_e32 v74, v56
	v_add_f32_e32 v239, v71, v239
	v_exp_f32_e32 v75, v57
	v_add_f32_e32 v239, v72, v239
	v_exp_f32_e32 v76, v58
	v_add_f32_e32 v239, v73, v239
	v_exp_f32_e32 v77, v59
	ds_read_b64_tr_b16 v[56:57], v238 offset:18496
	ds_read_b64_tr_b16 v[58:59], v238 offset:19648
	v_add_f32_e32 v239, v74, v239
	v_exp_f32_e32 v78, v60
	v_add_f32_e32 v239, v75, v239
	v_exp_f32_e32 v79, v61
	v_add_f32_e32 v239, v76, v239
	v_exp_f32_e32 v80, v62
	v_add_f32_e32 v239, v77, v239
	v_exp_f32_e32 v81, v63
	ds_read_b64_tr_b16 v[60:61], v238 offset:20800
	ds_read_b64_tr_b16 v[62:63], v238 offset:21952
	v_add_f32_e32 v239, v78, v239
	v_add_f32_e32 v239, v79, v239
	v_add_f32_e32 v239, v80, v239
	v_add_f32_e32 v239, v81, v239
	v_mov_b32_e32 v240, v239
	s_nop 1
	v_permlane32_swap_b32_e32 v239, v240
	v_add_f32_e32 v239, v239, v240
	v_add_f32_e32 v64, v64, v239
	v_cvt_pk_bf16_f32 v66, v66, v67
	v_cvt_pk_bf16_f32 v67, v68, v69
	v_cvt_pk_bf16_f32 v68, v70, v71
	v_cvt_pk_bf16_f32 v69, v72, v73
	v_cvt_pk_bf16_f32 v70, v74, v75
	v_cvt_pk_bf16_f32 v71, v76, v77
	s_waitcnt lgkmcnt(6)
	v_mfma_f32_32x32x16_bf16 v[0:15], v[48:51], v[66:69], v[0:15]
	v_cvt_pk_bf16_f32 v72, v78, v79
	v_cvt_pk_bf16_f32 v73, v80, v81
	s_waitcnt lgkmcnt(2)
	v_mfma_f32_32x32x16_bf16 v[16:31], v[56:59], v[66:69], v[16:31]
	s_nop 0
	v_mfma_f32_32x32x16_bf16 v[0:15], v[52:55], v[70:73], v[0:15]
	s_waitcnt lgkmcnt(0)
	v_mfma_f32_32x32x16_bf16 v[16:31], v[60:63], v[70:73], v[16:31]
